# strategy 4 extended: static s_setprio 1 for waves 4-7 also in P1, S5 passes and attention (reset at every grid barrier)
# baseline (speedup 1.0000x reference)
.LBB0_104:
	s_cmp_ge_u32 s95, 4
	s_cbranch_scc0 .Lpr_0
	s_setprio 1
